# adds a straight-line rope+scale epilogue for the uq GEMM (same operations as the dispatching path) to the previous version
# baseline (speedup 1.0000x reference)
;     __device__ __forceinline__ void operator()(const f32x4 (&acc)[2][2][4][2], const Unit& u, int wr, int wc, int fr_in, int fq_in) const {
;     ...
;             bool rope = false; int i0 = 0, tw = 64; float sc = 1.f;
;             if (mode == EM_QKVA) { rope = c < 2560; i0 = (c & 127) >> 1; tw = 64; sc = c < 2048 ? QS_A : 1.f; }
;             else if (mode == EM_UQ) { const int hc = c % 192; rope = hc >= 128; i0 = (hc - 128) >> 1; tw = 32; sc = QS_B; }
.LBB0_274:
	s_cmp_eq_u32 s56, 3
	s_mov_b64 s[8:9], 0
	s_cbranch_scc0 .LBB0_358
	s_mov_b32 s0, 0x2aaaaaab
	v_mul_hi_i32 v128, v232, s0
	v_lshrrev_b32_e32 v129, 31, v128
	v_lshrrev_b32_e32 v128, 5, v128
	v_add_u32_e32 v128, v128, v129
	s_movk_i32 s0, 0xc0
	v_mul_lo_u32 v128, v128, s0
	v_sub_u32_e32 v128, v232, v128
	v_cmp_lt_i32_e32 vcc, s97, v128
	v_add_u32_e32 v128, 0xffffff80, v128
	v_ashrrev_i32_e32 v242, 1, v128
	s_mov_b32 s65, 32
	s_mov_b32 s33, 0x3dd53b94
	s_and_b64 s[0:1], vcc, exec
	s_and_b64 vcc, exec, s[40:41]
	s_cbranch_vccnz .Lepi_uq
	s_branch .LBB0_359

;     __device__ __forceinline__ void operator()(const f32x4 (&acc)[2][2][4][2], const Unit& u, int wr, int wc, int fr_in, int fq_in) const {
;     ...
;             for (int ai = 0; ai < 2; ++ai) {
;                 f32x4 rc[4], rsn[4];
;                 if (rope) {
; #pragma unroll
;                     for (int m = 0; m < 4; ++m) { const int pos = row_pos(row0 + ai * HALF + m * 16); const unsigned tb = (unsigned)(pos * tw + i0) * 4u; rc[m] = *(const f32x4*)((const char*)cosT + tb); rsn[m] = *(const f32x4*)((const char*)sinT + tb); }
;                 }
; #pragma unroll
;                 for (int m = 0; m < 4; ++m) {
;                     const int row = row0 + ai * HALF + m * 16;
;                     f32x4 v0 = acc[ai][bj][m][0], v1 = acc[ai][bj][m][1];
;                     if (lnin) { const float mm = mu[ai * 4 + m], rr = rs[ai * 4 + m]; v0 = (v0 - cs0 * mm) * rr + bw0; v1 = (v1 - cs1 * mm) * rr + bw1; }
;                     if (mode == EM_F32) { const unsigned ob = (unsigned)(row * ldo + c) * 4u; *(f32x4*)((char*)Of + ob) = v0; *(f32x4*)((char*)Of + ob + 16u) = v1; }
;                     else {
;                         if (mode == EM_RELU2) {
; #pragma unroll
;                             for (int e = 0; e < 4; ++e) { const float a = fmaxf(v0[e], 0.f), b = fmaxf(v1[e], 0.f); v0[e] = a * a; v1[e] = b * b; }
;                         } else if (mode == EM_QKVA || mode == EM_UQ) {
;                             if (rope) {
;                                 const f32x4 cs_ = rc[m], sn = rsn[m];
;                                 f32x4 w0, w1;
;                                 w0[0] = v0[0] * cs_[0] - v0[1] * sn[0]; w0[1] = v0[1] * cs_[0] + v0[0] * sn[0];
;                                 w0[2] = v0[2] * cs_[1] - v0[3] * sn[1]; w0[3] = v0[3] * cs_[1] + v0[2] * sn[1];
;                                 w1[0] = v1[0] * cs_[2] - v1[1] * sn[2]; w1[1] = v1[1] * cs_[2] + v1[0] * sn[2];
;                                 w1[2] = v1[2] * cs_[3] - v1[3] * sn[3]; w1[3] = v1[3] * cs_[3] + v1[2] * sn[3];
;                                 v0 = w0; v1 = w1;
;                             }
;                             v0 = v0 * sc; v1 = v1 * sc;
;                         }
;                         u32x4 w; w.x = cvt_pk_bf16(v0[0], v0[1]); w.y = cvt_pk_bf16(v0[2], v0[3]); w.z = cvt_pk_bf16(v1[0], v1[1]); w.w = cvt_pk_bf16(v1[2], v1[3]);
.Lepi_uq:
	v_mov_b32_e32 v234, s33
	v_mov_b32_e32 v235, s33
	v_mov_b32_e32 v214, v242
	v_mul_lo_u32 v189, v236, s55
	v_add_lshl_u32 v206, v189, v232, 1
	s_lshl_b32 s34, s55, 5
	v_add_u32_e32 v207, s34, v206
	s_lshl_b32 s35, s55, 6
	v_add_u32_e32 v208, s35, v206
	s_add_i32 s35, s35, s34
	v_add_u32_e32 v209, s35, v206
	s_lshl_b32 s35, s55, 8
	v_add_u32_e32 v210, s35, v206
	v_add_u32_e32 v211, s35, v207
	v_add_u32_e32 v212, s35, v208
	v_add_u32_e32 v213, s35, v209
	v_mov_b32_e32 v215, 0xfff
	v_mov_b32_e32 v216, 0x1fff
	s_movk_i32 s34, 0x4000
	v_cmp_gt_i32_e32 vcc, s34, v236
	v_cndmask_b32_e32 v215, v215, v216, vcc
	s_and_saveexec_b64 s[8:9], s[0:1]
	s_cbranch_execz .Luq_nl_0_0
	v_mov_b32_e32 v216, v236
	v_and_b32_e32 v216, v216, v215
	v_mul_u32_u24_e32 v216, 32, v216
	v_add_lshl_u32 v216, v216, v214, 2
	global_load_dwordx4 v[152:155], v216, s[6:7]
	global_load_dwordx4 v[156:159], v216, s[4:5]
	v_add_u32_e32 v216, 0x10, v236
	v_and_b32_e32 v216, v216, v215
	v_mul_u32_u24_e32 v216, 32, v216
	v_add_lshl_u32 v216, v216, v214, 2
	global_load_dwordx4 v[144:147], v216, s[6:7]
	global_load_dwordx4 v[148:151], v216, s[4:5]
	v_add_u32_e32 v216, 0x20, v236
	v_and_b32_e32 v216, v216, v215
	v_mul_u32_u24_e32 v216, 32, v216
	v_add_lshl_u32 v216, v216, v214, 2
	global_load_dwordx4 v[140:143], v216, s[6:7]
	global_load_dwordx4 v[136:139], v216, s[4:5]
	v_add_u32_e32 v216, 0x30, v236
	v_and_b32_e32 v216, v216, v215
	v_mul_u32_u24_e32 v216, 32, v216
	v_add_lshl_u32 v216, v216, v214, 2
	global_load_dwordx4 v[128:131], v216, s[6:7]
	global_load_dwordx4 v[132:135], v216, s[4:5]
.Luq_nl_0_0:
	s_or_b64 exec, exec, s[8:9]
	v_mov_b32_e32 v184, v124
	v_mov_b32_e32 v185, v125
	v_mov_b32_e32 v186, v126
	v_mov_b32_e32 v187, v127
	v_mov_b32_e32 v188, v120
	v_mov_b32_e32 v189, v121
	v_mov_b32_e32 v190, v122
	v_mov_b32_e32 v191, v123
	s_and_saveexec_b64 s[8:9], s[0:1]
	s_cbranch_execz .Luq_nr_0
	s_waitcnt vmcnt(6)
	v_pk_mul_f32 v[186:187], v[156:157], v[124:125] op_sel:[0,1] op_sel_hi:[0,0]
	v_pk_fma_f32 v[188:189], v[152:153], v[124:125], v[186:187] op_sel_hi:[0,1,1]
	v_pk_fma_f32 v[184:185], v[152:153], v[124:125], v[186:187] op_sel_hi:[0,1,1] neg_lo:[0,0,1] neg_hi:[0,0,1]
	v_mov_b32_e32 v186, v153
	v_mov_b32_e32 v187, v157
	v_mul_f32_e32 v188, v157, v127
	v_pk_fma_f32 v[186:187], v[186:187], v[126:127], v[188:189] op_sel_hi:[1,1,0] neg_lo:[0,0,1] neg_hi:[0,0,1]
	v_mov_b32_e32 v190, v157
	v_mov_b32_e32 v191, v153
	v_mul_f32_e32 v188, v153, v127
	v_pk_fma_f32 v[190:191], v[190:191], v[126:127], v[188:189] op_sel_hi:[1,1,0]
	v_mov_b32_e32 v185, v189
	v_mov_b32_e32 v187, v190
	v_pk_mul_f32 v[190:191], v[158:159], v[120:121] op_sel:[0,1] op_sel_hi:[0,0]
	v_pk_fma_f32 v[188:189], v[154:155], v[120:121], v[190:191] op_sel_hi:[0,1,1] neg_lo:[0,0,1] neg_hi:[0,0,1]
	v_pk_fma_f32 v[224:225], v[154:155], v[120:121], v[190:191] op_sel_hi:[0,1,1]
	v_mov_b32_e32 v190, v155
	v_mov_b32_e32 v191, v159
	v_mul_f32_e32 v192, v159, v123
	v_pk_fma_f32 v[190:191], v[190:191], v[122:123], v[192:193] op_sel_hi:[1,1,0] neg_lo:[0,0,1] neg_hi:[0,0,1]
	v_mov_b32_e32 v226, v159
	v_mov_b32_e32 v227, v155
	v_mul_f32_e32 v192, v155, v123
	v_pk_fma_f32 v[226:227], v[226:227], v[122:123], v[192:193] op_sel_hi:[1,1,0]
	v_mov_b32_e32 v189, v225
	v_mov_b32_e32 v191, v226
.Luq_nr_0:
	s_or_b64 exec, exec, s[8:9]
	v_pk_mul_f32 v[224:225], v[234:235], v[186:187]
	v_pk_mul_f32 v[226:227], v[234:235], v[184:185]
	v_pk_mul_f32 v[184:185], v[234:235], v[190:191]
	v_pk_mul_f32 v[186:187], v[234:235], v[188:189]
	v_cvt_pk_bf16_f32 v160, v226, v227
	v_cvt_pk_bf16_f32 v161, v224, v225
	v_cvt_pk_bf16_f32 v162, v186, v187
	v_cvt_pk_bf16_f32 v163, v184, v185
	global_store_dwordx4 v206, v[160:163], s[50:51]
	v_mov_b32_e32 v184, v116
	v_mov_b32_e32 v185, v117
	v_mov_b32_e32 v186, v118
	v_mov_b32_e32 v187, v119
	v_mov_b32_e32 v188, v112
	v_mov_b32_e32 v189, v113
	v_mov_b32_e32 v190, v114
	v_mov_b32_e32 v191, v115
	s_and_saveexec_b64 s[8:9], s[0:1]
	s_cbranch_execz .Luq_nr_1
	s_waitcnt vmcnt(5)
	v_pk_mul_f32 v[186:187], v[148:149], v[116:117] op_sel:[0,1] op_sel_hi:[0,0]
	v_pk_fma_f32 v[188:189], v[144:145], v[116:117], v[186:187] op_sel_hi:[0,1,1]
	v_pk_fma_f32 v[184:185], v[144:145], v[116:117], v[186:187] op_sel_hi:[0,1,1] neg_lo:[0,0,1] neg_hi:[0,0,1]
	v_mov_b32_e32 v186, v145
	v_mov_b32_e32 v187, v149
	v_mul_f32_e32 v188, v149, v119
	v_pk_fma_f32 v[186:187], v[186:187], v[118:119], v[188:189] op_sel_hi:[1,1,0] neg_lo:[0,0,1] neg_hi:[0,0,1]
	v_mov_b32_e32 v190, v149
	v_mov_b32_e32 v191, v145
	v_mul_f32_e32 v188, v145, v119
	v_pk_fma_f32 v[190:191], v[190:191], v[118:119], v[188:189] op_sel_hi:[1,1,0]
	v_mov_b32_e32 v185, v189
	v_mov_b32_e32 v187, v190
	v_pk_mul_f32 v[190:191], v[150:151], v[112:113] op_sel:[0,1] op_sel_hi:[0,0]
	v_pk_fma_f32 v[188:189], v[146:147], v[112:113], v[190:191] op_sel_hi:[0,1,1] neg_lo:[0,0,1] neg_hi:[0,0,1]
	v_pk_fma_f32 v[224:225], v[146:147], v[112:113], v[190:191] op_sel_hi:[0,1,1]
	v_mov_b32_e32 v190, v147
	v_mov_b32_e32 v191, v151
	v_mul_f32_e32 v192, v151, v115
	v_pk_fma_f32 v[190:191], v[190:191], v[114:115], v[192:193] op_sel_hi:[1,1,0] neg_lo:[0,0,1] neg_hi:[0,0,1]
	v_mov_b32_e32 v226, v151
	v_mov_b32_e32 v227, v147
	v_mul_f32_e32 v192, v147, v115
	v_pk_fma_f32 v[226:227], v[226:227], v[114:115], v[192:193] op_sel_hi:[1,1,0]
	v_mov_b32_e32 v189, v225
	v_mov_b32_e32 v191, v226
;     __device__ __forceinline__ void operator()(const f32x4 (&acc)[2][2][4][2], const Unit& u, int wr, int wc, int fr_in, int fq_in) const {
;     ...
;                 if (rope) {
; #pragma unroll
;                     for (int m = 0; m < 4; ++m) { const int pos = row_pos(row0 + ai * HALF + m * 16); const unsigned tb = (unsigned)(pos * tw + i0) * 4u; rc[m] = *(const f32x4*)((const char*)cosT + tb); rsn[m] = *(const f32x4*)((const char*)sinT + tb); }
;                 }
; #pragma unroll
;                 for (int m = 0; m < 4; ++m) {
;                     const int row = row0 + ai * HALF + m * 16;
;                     f32x4 v0 = acc[ai][bj][m][0], v1 = acc[ai][bj][m][1];
;                     if (lnin) { const float mm = mu[ai * 4 + m], rr = rs[ai * 4 + m]; v0 = (v0 - cs0 * mm) * rr + bw0; v1 = (v1 - cs1 * mm) * rr + bw1; }
;                     if (mode == EM_F32) { const unsigned ob = (unsigned)(row * ldo + c) * 4u; *(f32x4*)((char*)Of + ob) = v0; *(f32x4*)((char*)Of + ob + 16u) = v1; }
;                     else {
;                         if (mode == EM_RELU2) {
; #pragma unroll
;                             for (int e = 0; e < 4; ++e) { const float a = fmaxf(v0[e], 0.f), b = fmaxf(v1[e], 0.f); v0[e] = a * a; v1[e] = b * b; }
;                         } else if (mode == EM_QKVA || mode == EM_UQ) {
;                             if (rope) {
;                                 const f32x4 cs_ = rc[m], sn = rsn[m];
;                                 f32x4 w0, w1;
;                                 w0[0] = v0[0] * cs_[0] - v0[1] * sn[0]; w0[1] = v0[1] * cs_[0] + v0[0] * sn[0];
;                                 w0[2] = v0[2] * cs_[1] - v0[3] * sn[1]; w0[3] = v0[3] * cs_[1] + v0[2] * sn[1];
;                                 w1[0] = v1[0] * cs_[2] - v1[1] * sn[2]; w1[1] = v1[1] * cs_[2] + v1[0] * sn[2];
;                                 w1[2] = v1[2] * cs_[3] - v1[3] * sn[3]; w1[3] = v1[3] * cs_[3] + v1[2] * sn[3];
;                                 v0 = w0; v1 = w1;
;                             }
;                             v0 = v0 * sc; v1 = v1 * sc;
;                         }
;                         u32x4 w; w.x = cvt_pk_bf16(v0[0], v0[1]); w.y = cvt_pk_bf16(v0[2], v0[3]); w.z = cvt_pk_bf16(v1[0], v1[1]); w.w = cvt_pk_bf16(v1[2], v1[3]);
.Luq_nr_1:
	s_or_b64 exec, exec, s[8:9]
	v_pk_mul_f32 v[224:225], v[234:235], v[186:187]
	v_pk_mul_f32 v[226:227], v[234:235], v[184:185]
	v_pk_mul_f32 v[184:185], v[234:235], v[190:191]
	v_pk_mul_f32 v[186:187], v[234:235], v[188:189]
	v_cvt_pk_bf16_f32 v164, v226, v227
	v_cvt_pk_bf16_f32 v165, v224, v225
	v_cvt_pk_bf16_f32 v166, v186, v187
	v_cvt_pk_bf16_f32 v167, v184, v185
	global_store_dwordx4 v207, v[164:167], s[50:51]
	v_mov_b32_e32 v184, v108
	v_mov_b32_e32 v185, v109
	v_mov_b32_e32 v186, v110
	v_mov_b32_e32 v187, v111
	v_mov_b32_e32 v188, v104
	v_mov_b32_e32 v189, v105
	v_mov_b32_e32 v190, v106
	v_mov_b32_e32 v191, v107
	s_and_saveexec_b64 s[8:9], s[0:1]
	s_cbranch_execz .Luq_nr_2
	s_waitcnt vmcnt(4)
	v_pk_mul_f32 v[186:187], v[136:137], v[108:109] op_sel:[0,1] op_sel_hi:[0,0]
	v_pk_fma_f32 v[188:189], v[140:141], v[108:109], v[186:187] op_sel_hi:[0,1,1]
	v_pk_fma_f32 v[184:185], v[140:141], v[108:109], v[186:187] op_sel_hi:[0,1,1] neg_lo:[0,0,1] neg_hi:[0,0,1]
	v_mov_b32_e32 v186, v141
	v_mov_b32_e32 v187, v137
	v_mul_f32_e32 v188, v137, v111
	v_pk_fma_f32 v[186:187], v[186:187], v[110:111], v[188:189] op_sel_hi:[1,1,0] neg_lo:[0,0,1] neg_hi:[0,0,1]
	v_mov_b32_e32 v190, v137
	v_mov_b32_e32 v191, v141
	v_mul_f32_e32 v188, v141, v111
	v_pk_fma_f32 v[190:191], v[190:191], v[110:111], v[188:189] op_sel_hi:[1,1,0]
	v_mov_b32_e32 v185, v189
	v_mov_b32_e32 v187, v190
	v_pk_mul_f32 v[190:191], v[138:139], v[104:105] op_sel:[0,1] op_sel_hi:[0,0]
	v_pk_fma_f32 v[188:189], v[142:143], v[104:105], v[190:191] op_sel_hi:[0,1,1] neg_lo:[0,0,1] neg_hi:[0,0,1]
	v_pk_fma_f32 v[224:225], v[142:143], v[104:105], v[190:191] op_sel_hi:[0,1,1]
	v_mov_b32_e32 v190, v143
	v_mov_b32_e32 v191, v139
	v_mul_f32_e32 v192, v139, v107
	v_pk_fma_f32 v[190:191], v[190:191], v[106:107], v[192:193] op_sel_hi:[1,1,0] neg_lo:[0,0,1] neg_hi:[0,0,1]
	v_mov_b32_e32 v226, v139
	v_mov_b32_e32 v227, v143
	v_mul_f32_e32 v192, v143, v107
	v_pk_fma_f32 v[226:227], v[226:227], v[106:107], v[192:193] op_sel_hi:[1,1,0]
	v_mov_b32_e32 v189, v225
	v_mov_b32_e32 v191, v226
.Luq_nr_2:
	s_or_b64 exec, exec, s[8:9]
	v_pk_mul_f32 v[224:225], v[234:235], v[186:187]
	v_pk_mul_f32 v[226:227], v[234:235], v[184:185]
	v_pk_mul_f32 v[184:185], v[234:235], v[190:191]
	v_pk_mul_f32 v[186:187], v[234:235], v[188:189]
	v_cvt_pk_bf16_f32 v168, v226, v227
	v_cvt_pk_bf16_f32 v169, v224, v225
	v_cvt_pk_bf16_f32 v170, v186, v187
	v_cvt_pk_bf16_f32 v171, v184, v185
	global_store_dwordx4 v208, v[168:171], s[50:51]
	v_mov_b32_e32 v184, v100
	v_mov_b32_e32 v185, v101
	v_mov_b32_e32 v186, v102
	v_mov_b32_e32 v187, v103
	v_mov_b32_e32 v188, v96
	v_mov_b32_e32 v189, v97
	v_mov_b32_e32 v190, v98
	v_mov_b32_e32 v191, v99
	s_and_saveexec_b64 s[8:9], s[0:1]
	s_cbranch_execz .Luq_nr_3
	s_waitcnt vmcnt(3)
	v_pk_mul_f32 v[186:187], v[132:133], v[100:101] op_sel:[0,1] op_sel_hi:[0,0]
	v_pk_fma_f32 v[188:189], v[128:129], v[100:101], v[186:187] op_sel_hi:[0,1,1]
	v_pk_fma_f32 v[184:185], v[128:129], v[100:101], v[186:187] op_sel_hi:[0,1,1] neg_lo:[0,0,1] neg_hi:[0,0,1]
	v_mov_b32_e32 v186, v129
	v_mov_b32_e32 v187, v133
	v_mul_f32_e32 v188, v133, v103
	v_pk_fma_f32 v[186:187], v[186:187], v[102:103], v[188:189] op_sel_hi:[1,1,0] neg_lo:[0,0,1] neg_hi:[0,0,1]
	v_mov_b32_e32 v190, v133
	v_mov_b32_e32 v191, v129
	v_mul_f32_e32 v188, v129, v103
	v_pk_fma_f32 v[190:191], v[190:191], v[102:103], v[188:189] op_sel_hi:[1,1,0]
	v_mov_b32_e32 v185, v189
	v_mov_b32_e32 v187, v190
	v_pk_mul_f32 v[190:191], v[134:135], v[96:97] op_sel:[0,1] op_sel_hi:[0,0]
	v_pk_fma_f32 v[188:189], v[130:131], v[96:97], v[190:191] op_sel_hi:[0,1,1] neg_lo:[0,0,1] neg_hi:[0,0,1]
	v_pk_fma_f32 v[224:225], v[130:131], v[96:97], v[190:191] op_sel_hi:[0,1,1]
	v_mov_b32_e32 v190, v131
	v_mov_b32_e32 v191, v135
	v_mul_f32_e32 v192, v135, v99
	v_pk_fma_f32 v[190:191], v[190:191], v[98:99], v[192:193] op_sel_hi:[1,1,0] neg_lo:[0,0,1] neg_hi:[0,0,1]
	v_mov_b32_e32 v226, v135
	v_mov_b32_e32 v227, v131
	v_mul_f32_e32 v192, v131, v99
	v_pk_fma_f32 v[226:227], v[226:227], v[98:99], v[192:193] op_sel_hi:[1,1,0]
	v_mov_b32_e32 v189, v225
	v_mov_b32_e32 v191, v226
.Luq_nr_3:
	s_or_b64 exec, exec, s[8:9]
	v_pk_mul_f32 v[224:225], v[234:235], v[186:187]
	v_pk_mul_f32 v[226:227], v[234:235], v[184:185]
	v_pk_mul_f32 v[184:185], v[234:235], v[190:191]
	v_pk_mul_f32 v[186:187], v[234:235], v[188:189]
	v_cvt_pk_bf16_f32 v172, v226, v227
	v_cvt_pk_bf16_f32 v173, v224, v225
	v_cvt_pk_bf16_f32 v174, v186, v187
	v_cvt_pk_bf16_f32 v175, v184, v185
	global_store_dwordx4 v209, v[172:175], s[50:51]
	s_and_saveexec_b64 s[8:9], s[0:1]
	s_cbranch_execz .Luq_nl_0_1
	v_add_u32_e32 v216, 0x80, v236
	v_and_b32_e32 v216, v216, v215
	v_mul_u32_u24_e32 v216, 32, v216
	v_add_lshl_u32 v216, v216, v214, 2
	global_load_dwordx4 v[152:155], v216, s[6:7]
	global_load_dwordx4 v[156:159], v216, s[4:5]
	v_add_u32_e32 v216, 0x90, v236
	v_and_b32_e32 v216, v216, v215
	v_mul_u32_u24_e32 v216, 32, v216
	v_add_lshl_u32 v216, v216, v214, 2
	global_load_dwordx4 v[144:147], v216, s[6:7]
	global_load_dwordx4 v[148:151], v216, s[4:5]
	v_add_u32_e32 v216, 0xa0, v236
	v_and_b32_e32 v216, v216, v215
	v_mul_u32_u24_e32 v216, 32, v216
	v_add_lshl_u32 v216, v216, v214, 2
	global_load_dwordx4 v[140:143], v216, s[6:7]
	global_load_dwordx4 v[136:139], v216, s[4:5]
	v_add_u32_e32 v216, 0xb0, v236
	v_and_b32_e32 v216, v216, v215
	v_mul_u32_u24_e32 v216, 32, v216
	v_add_lshl_u32 v216, v216, v214, 2
	global_load_dwordx4 v[128:131], v216, s[6:7]
	global_load_dwordx4 v[132:135], v216, s[4:5]
;     __device__ __forceinline__ void operator()(const f32x4 (&acc)[2][2][4][2], const Unit& u, int wr, int wc, int fr_in, int fq_in) const {
;     ...
;                 if (rope) {
; #pragma unroll
;                     for (int m = 0; m < 4; ++m) { const int pos = row_pos(row0 + ai * HALF + m * 16); const unsigned tb = (unsigned)(pos * tw + i0) * 4u; rc[m] = *(const f32x4*)((const char*)cosT + tb); rsn[m] = *(const f32x4*)((const char*)sinT + tb); }
;                 }
; #pragma unroll
;                 for (int m = 0; m < 4; ++m) {
;                     const int row = row0 + ai * HALF + m * 16;
;                     f32x4 v0 = acc[ai][bj][m][0], v1 = acc[ai][bj][m][1];
;                     if (lnin) { const float mm = mu[ai * 4 + m], rr = rs[ai * 4 + m]; v0 = (v0 - cs0 * mm) * rr + bw0; v1 = (v1 - cs1 * mm) * rr + bw1; }
;                     if (mode == EM_F32) { const unsigned ob = (unsigned)(row * ldo + c) * 4u; *(f32x4*)((char*)Of + ob) = v0; *(f32x4*)((char*)Of + ob + 16u) = v1; }
;                     else {
;                         if (mode == EM_RELU2) {
; #pragma unroll
;                             for (int e = 0; e < 4; ++e) { const float a = fmaxf(v0[e], 0.f), b = fmaxf(v1[e], 0.f); v0[e] = a * a; v1[e] = b * b; }
;                         } else if (mode == EM_QKVA || mode == EM_UQ) {
;                             if (rope) {
;                                 const f32x4 cs_ = rc[m], sn = rsn[m];
;                                 f32x4 w0, w1;
;                                 w0[0] = v0[0] * cs_[0] - v0[1] * sn[0]; w0[1] = v0[1] * cs_[0] + v0[0] * sn[0];
;                                 w0[2] = v0[2] * cs_[1] - v0[3] * sn[1]; w0[3] = v0[3] * cs_[1] + v0[2] * sn[1];
;                                 w1[0] = v1[0] * cs_[2] - v1[1] * sn[2]; w1[1] = v1[1] * cs_[2] + v1[0] * sn[2];
;                                 w1[2] = v1[2] * cs_[3] - v1[3] * sn[3]; w1[3] = v1[3] * cs_[3] + v1[2] * sn[3];
;                                 v0 = w0; v1 = w1;
;                             }
;                             v0 = v0 * sc; v1 = v1 * sc;
;                         }
;                         u32x4 w; w.x = cvt_pk_bf16(v0[0], v0[1]); w.y = cvt_pk_bf16(v0[2], v0[3]); w.z = cvt_pk_bf16(v1[0], v1[1]); w.w = cvt_pk_bf16(v1[2], v1[3]);
.Luq_nl_0_1:
	s_or_b64 exec, exec, s[8:9]
	v_mov_b32_e32 v184, v60
	v_mov_b32_e32 v185, v61
	v_mov_b32_e32 v186, v62
	v_mov_b32_e32 v187, v63
	v_mov_b32_e32 v188, v56
	v_mov_b32_e32 v189, v57
	v_mov_b32_e32 v190, v58
	v_mov_b32_e32 v191, v59
	s_and_saveexec_b64 s[8:9], s[0:1]
	s_cbranch_execz .Luq_nr_4
	s_waitcnt vmcnt(6)
	v_pk_mul_f32 v[186:187], v[156:157], v[60:61] op_sel:[0,1] op_sel_hi:[0,0]
	v_pk_fma_f32 v[188:189], v[152:153], v[60:61], v[186:187] op_sel_hi:[0,1,1]
	v_pk_fma_f32 v[184:185], v[152:153], v[60:61], v[186:187] op_sel_hi:[0,1,1] neg_lo:[0,0,1] neg_hi:[0,0,1]
	v_mov_b32_e32 v186, v153
	v_mov_b32_e32 v187, v157
	v_mul_f32_e32 v188, v157, v63
	v_pk_fma_f32 v[186:187], v[186:187], v[62:63], v[188:189] op_sel_hi:[1,1,0] neg_lo:[0,0,1] neg_hi:[0,0,1]
	v_mov_b32_e32 v190, v157
	v_mov_b32_e32 v191, v153
	v_mul_f32_e32 v188, v153, v63
	v_pk_fma_f32 v[190:191], v[190:191], v[62:63], v[188:189] op_sel_hi:[1,1,0]
	v_mov_b32_e32 v185, v189
	v_mov_b32_e32 v187, v190
	v_pk_mul_f32 v[190:191], v[158:159], v[56:57] op_sel:[0,1] op_sel_hi:[0,0]
	v_pk_fma_f32 v[188:189], v[154:155], v[56:57], v[190:191] op_sel_hi:[0,1,1] neg_lo:[0,0,1] neg_hi:[0,0,1]
	v_pk_fma_f32 v[224:225], v[154:155], v[56:57], v[190:191] op_sel_hi:[0,1,1]
	v_mov_b32_e32 v190, v155
	v_mov_b32_e32 v191, v159
	v_mul_f32_e32 v192, v159, v59
	v_pk_fma_f32 v[190:191], v[190:191], v[58:59], v[192:193] op_sel_hi:[1,1,0] neg_lo:[0,0,1] neg_hi:[0,0,1]
	v_mov_b32_e32 v226, v159
	v_mov_b32_e32 v227, v155
	v_mul_f32_e32 v192, v155, v59
	v_pk_fma_f32 v[226:227], v[226:227], v[58:59], v[192:193] op_sel_hi:[1,1,0]
	v_mov_b32_e32 v189, v225
	v_mov_b32_e32 v191, v226
.Luq_nr_4:
	s_or_b64 exec, exec, s[8:9]
	v_pk_mul_f32 v[224:225], v[234:235], v[186:187]
	v_pk_mul_f32 v[226:227], v[234:235], v[184:185]
	v_pk_mul_f32 v[184:185], v[234:235], v[190:191]
	v_pk_mul_f32 v[186:187], v[234:235], v[188:189]
	v_cvt_pk_bf16_f32 v160, v226, v227
	v_cvt_pk_bf16_f32 v161, v224, v225
	v_cvt_pk_bf16_f32 v162, v186, v187
	v_cvt_pk_bf16_f32 v163, v184, v185
	global_store_dwordx4 v210, v[160:163], s[50:51]
	v_mov_b32_e32 v184, v52
	v_mov_b32_e32 v185, v53
	v_mov_b32_e32 v186, v54
	v_mov_b32_e32 v187, v55
	v_mov_b32_e32 v188, v48
	v_mov_b32_e32 v189, v49
	v_mov_b32_e32 v190, v50
	v_mov_b32_e32 v191, v51
	s_and_saveexec_b64 s[8:9], s[0:1]
	s_cbranch_execz .Luq_nr_5
	s_waitcnt vmcnt(5)
	v_pk_mul_f32 v[186:187], v[148:149], v[52:53] op_sel:[0,1] op_sel_hi:[0,0]
	v_pk_fma_f32 v[188:189], v[144:145], v[52:53], v[186:187] op_sel_hi:[0,1,1]
	v_pk_fma_f32 v[184:185], v[144:145], v[52:53], v[186:187] op_sel_hi:[0,1,1] neg_lo:[0,0,1] neg_hi:[0,0,1]
	v_mov_b32_e32 v186, v145
	v_mov_b32_e32 v187, v149
	v_mul_f32_e32 v188, v149, v55
	v_pk_fma_f32 v[186:187], v[186:187], v[54:55], v[188:189] op_sel_hi:[1,1,0] neg_lo:[0,0,1] neg_hi:[0,0,1]
	v_mov_b32_e32 v190, v149
	v_mov_b32_e32 v191, v145
	v_mul_f32_e32 v188, v145, v55
	v_pk_fma_f32 v[190:191], v[190:191], v[54:55], v[188:189] op_sel_hi:[1,1,0]
	v_mov_b32_e32 v185, v189
	v_mov_b32_e32 v187, v190
	v_pk_mul_f32 v[190:191], v[150:151], v[48:49] op_sel:[0,1] op_sel_hi:[0,0]
	v_pk_fma_f32 v[188:189], v[146:147], v[48:49], v[190:191] op_sel_hi:[0,1,1] neg_lo:[0,0,1] neg_hi:[0,0,1]
	v_pk_fma_f32 v[224:225], v[146:147], v[48:49], v[190:191] op_sel_hi:[0,1,1]
	v_mov_b32_e32 v190, v147
	v_mov_b32_e32 v191, v151
	v_mul_f32_e32 v192, v151, v51
	v_pk_fma_f32 v[190:191], v[190:191], v[50:51], v[192:193] op_sel_hi:[1,1,0] neg_lo:[0,0,1] neg_hi:[0,0,1]
	v_mov_b32_e32 v226, v151
	v_mov_b32_e32 v227, v147
	v_mul_f32_e32 v192, v147, v51
	v_pk_fma_f32 v[226:227], v[226:227], v[50:51], v[192:193] op_sel_hi:[1,1,0]
	v_mov_b32_e32 v189, v225
	v_mov_b32_e32 v191, v226
.Luq_nr_5:
	s_or_b64 exec, exec, s[8:9]
	v_pk_mul_f32 v[224:225], v[234:235], v[186:187]
	v_pk_mul_f32 v[226:227], v[234:235], v[184:185]
	v_pk_mul_f32 v[184:185], v[234:235], v[190:191]
	v_pk_mul_f32 v[186:187], v[234:235], v[188:189]
	v_cvt_pk_bf16_f32 v164, v226, v227
	v_cvt_pk_bf16_f32 v165, v224, v225
	v_cvt_pk_bf16_f32 v166, v186, v187
	v_cvt_pk_bf16_f32 v167, v184, v185
	global_store_dwordx4 v211, v[164:167], s[50:51]
	v_mov_b32_e32 v184, v44
	v_mov_b32_e32 v185, v45
	v_mov_b32_e32 v186, v46
	v_mov_b32_e32 v187, v47
	v_mov_b32_e32 v188, v40
	v_mov_b32_e32 v189, v41
	v_mov_b32_e32 v190, v42
	v_mov_b32_e32 v191, v43
	s_and_saveexec_b64 s[8:9], s[0:1]
	s_cbranch_execz .Luq_nr_6
	s_waitcnt vmcnt(4)
	v_pk_mul_f32 v[186:187], v[136:137], v[44:45] op_sel:[0,1] op_sel_hi:[0,0]
	v_pk_fma_f32 v[188:189], v[140:141], v[44:45], v[186:187] op_sel_hi:[0,1,1]
	v_pk_fma_f32 v[184:185], v[140:141], v[44:45], v[186:187] op_sel_hi:[0,1,1] neg_lo:[0,0,1] neg_hi:[0,0,1]
	v_mov_b32_e32 v186, v141
	v_mov_b32_e32 v187, v137
	v_mul_f32_e32 v188, v137, v47
	v_pk_fma_f32 v[186:187], v[186:187], v[46:47], v[188:189] op_sel_hi:[1,1,0] neg_lo:[0,0,1] neg_hi:[0,0,1]
	v_mov_b32_e32 v190, v137
	v_mov_b32_e32 v191, v141
	v_mul_f32_e32 v188, v141, v47
	v_pk_fma_f32 v[190:191], v[190:191], v[46:47], v[188:189] op_sel_hi:[1,1,0]
	v_mov_b32_e32 v185, v189
	v_mov_b32_e32 v187, v190
	v_pk_mul_f32 v[190:191], v[138:139], v[40:41] op_sel:[0,1] op_sel_hi:[0,0]
	v_pk_fma_f32 v[188:189], v[142:143], v[40:41], v[190:191] op_sel_hi:[0,1,1] neg_lo:[0,0,1] neg_hi:[0,0,1]
	v_pk_fma_f32 v[224:225], v[142:143], v[40:41], v[190:191] op_sel_hi:[0,1,1]
	v_mov_b32_e32 v190, v143
	v_mov_b32_e32 v191, v139
	v_mul_f32_e32 v192, v139, v43
	v_pk_fma_f32 v[190:191], v[190:191], v[42:43], v[192:193] op_sel_hi:[1,1,0] neg_lo:[0,0,1] neg_hi:[0,0,1]
	v_mov_b32_e32 v226, v139
	v_mov_b32_e32 v227, v143
	v_mul_f32_e32 v192, v143, v43
	v_pk_fma_f32 v[226:227], v[226:227], v[42:43], v[192:193] op_sel_hi:[1,1,0]
	v_mov_b32_e32 v189, v225
	v_mov_b32_e32 v191, v226
;     __device__ __forceinline__ void operator()(const f32x4 (&acc)[2][2][4][2], const Unit& u, int wr, int wc, int fr_in, int fq_in) const {
;     ...
;             else if (mode == EM_UQ) { const int hc = c % 192; rope = hc >= 128; i0 = (hc - 128) >> 1; tw = 32; sc = QS_B; }
;     ...
;                 if (rope) {
; #pragma unroll
;                     for (int m = 0; m < 4; ++m) { const int pos = row_pos(row0 + ai * HALF + m * 16); const unsigned tb = (unsigned)(pos * tw + i0) * 4u; rc[m] = *(const f32x4*)((const char*)cosT + tb); rsn[m] = *(const f32x4*)((const char*)sinT + tb); }
;                 }
; #pragma unroll
;                 for (int m = 0; m < 4; ++m) {
;                     const int row = row0 + ai * HALF + m * 16;
;                     f32x4 v0 = acc[ai][bj][m][0], v1 = acc[ai][bj][m][1];
;                     if (lnin) { const float mm = mu[ai * 4 + m], rr = rs[ai * 4 + m]; v0 = (v0 - cs0 * mm) * rr + bw0; v1 = (v1 - cs1 * mm) * rr + bw1; }
;                     if (mode == EM_F32) { const unsigned ob = (unsigned)(row * ldo + c) * 4u; *(f32x4*)((char*)Of + ob) = v0; *(f32x4*)((char*)Of + ob + 16u) = v1; }
;                     else {
;                         if (mode == EM_RELU2) {
; #pragma unroll
;                             for (int e = 0; e < 4; ++e) { const float a = fmaxf(v0[e], 0.f), b = fmaxf(v1[e], 0.f); v0[e] = a * a; v1[e] = b * b; }
;                         } else if (mode == EM_QKVA || mode == EM_UQ) {
;                             if (rope) {
;                                 const f32x4 cs_ = rc[m], sn = rsn[m];
;                                 f32x4 w0, w1;
;                                 w0[0] = v0[0] * cs_[0] - v0[1] * sn[0]; w0[1] = v0[1] * cs_[0] + v0[0] * sn[0];
;                                 w0[2] = v0[2] * cs_[1] - v0[3] * sn[1]; w0[3] = v0[3] * cs_[1] + v0[2] * sn[1];
;                                 w1[0] = v1[0] * cs_[2] - v1[1] * sn[2]; w1[1] = v1[1] * cs_[2] + v1[0] * sn[2];
;                                 w1[2] = v1[2] * cs_[3] - v1[3] * sn[3]; w1[3] = v1[3] * cs_[3] + v1[2] * sn[3];
;                                 v0 = w0; v1 = w1;
;                             }
;                             v0 = v0 * sc; v1 = v1 * sc;
;                         }
;                         u32x4 w; w.x = cvt_pk_bf16(v0[0], v0[1]); w.y = cvt_pk_bf16(v0[2], v0[3]); w.z = cvt_pk_bf16(v1[0], v1[1]); w.w = cvt_pk_bf16(v1[2], v1[3]);
.Luq_nr_6:
	s_or_b64 exec, exec, s[8:9]
	v_pk_mul_f32 v[224:225], v[234:235], v[186:187]
	v_pk_mul_f32 v[226:227], v[234:235], v[184:185]
	v_pk_mul_f32 v[184:185], v[234:235], v[190:191]
	v_pk_mul_f32 v[186:187], v[234:235], v[188:189]
	v_cvt_pk_bf16_f32 v168, v226, v227
	v_cvt_pk_bf16_f32 v169, v224, v225
	v_cvt_pk_bf16_f32 v170, v186, v187
	v_cvt_pk_bf16_f32 v171, v184, v185
	global_store_dwordx4 v212, v[168:171], s[50:51]
	v_mov_b32_e32 v184, v36
	v_mov_b32_e32 v185, v37
	v_mov_b32_e32 v186, v38
	v_mov_b32_e32 v187, v39
	v_mov_b32_e32 v188, v32
	v_mov_b32_e32 v189, v33
	v_mov_b32_e32 v190, v34
	v_mov_b32_e32 v191, v35
	s_and_saveexec_b64 s[8:9], s[0:1]
	s_cbranch_execz .Luq_nr_7
	s_waitcnt vmcnt(3)
	v_pk_mul_f32 v[186:187], v[132:133], v[36:37] op_sel:[0,1] op_sel_hi:[0,0]
	v_pk_fma_f32 v[188:189], v[128:129], v[36:37], v[186:187] op_sel_hi:[0,1,1]
	v_pk_fma_f32 v[184:185], v[128:129], v[36:37], v[186:187] op_sel_hi:[0,1,1] neg_lo:[0,0,1] neg_hi:[0,0,1]
	v_mov_b32_e32 v186, v129
	v_mov_b32_e32 v187, v133
	v_mul_f32_e32 v188, v133, v39
	v_pk_fma_f32 v[186:187], v[186:187], v[38:39], v[188:189] op_sel_hi:[1,1,0] neg_lo:[0,0,1] neg_hi:[0,0,1]
	v_mov_b32_e32 v190, v133
	v_mov_b32_e32 v191, v129
	v_mul_f32_e32 v188, v129, v39
	v_pk_fma_f32 v[190:191], v[190:191], v[38:39], v[188:189] op_sel_hi:[1,1,0]
	v_mov_b32_e32 v185, v189
	v_mov_b32_e32 v187, v190
	v_pk_mul_f32 v[190:191], v[134:135], v[32:33] op_sel:[0,1] op_sel_hi:[0,0]
	v_pk_fma_f32 v[188:189], v[130:131], v[32:33], v[190:191] op_sel_hi:[0,1,1] neg_lo:[0,0,1] neg_hi:[0,0,1]
	v_pk_fma_f32 v[224:225], v[130:131], v[32:33], v[190:191] op_sel_hi:[0,1,1]
	v_mov_b32_e32 v190, v131
	v_mov_b32_e32 v191, v135
	v_mul_f32_e32 v192, v135, v35
	v_pk_fma_f32 v[190:191], v[190:191], v[34:35], v[192:193] op_sel_hi:[1,1,0] neg_lo:[0,0,1] neg_hi:[0,0,1]
	v_mov_b32_e32 v226, v135
	v_mov_b32_e32 v227, v131
	v_mul_f32_e32 v192, v131, v35
	v_pk_fma_f32 v[226:227], v[226:227], v[34:35], v[192:193] op_sel_hi:[1,1,0]
	v_mov_b32_e32 v189, v225
	v_mov_b32_e32 v191, v226
.Luq_nr_7:
	s_or_b64 exec, exec, s[8:9]
	v_pk_mul_f32 v[224:225], v[234:235], v[186:187]
	v_pk_mul_f32 v[226:227], v[234:235], v[184:185]
	v_pk_mul_f32 v[184:185], v[234:235], v[190:191]
	v_pk_mul_f32 v[186:187], v[234:235], v[188:189]
	v_cvt_pk_bf16_f32 v172, v226, v227
	v_cvt_pk_bf16_f32 v173, v224, v225
	v_cvt_pk_bf16_f32 v174, v186, v187
	v_cvt_pk_bf16_f32 v175, v184, v185
	global_store_dwordx4 v213, v[172:175], s[50:51]
	v_add_u32_e32 v227, 0x80, v232
	s_mov_b32 s34, 0x2aaaaaab
	v_mul_hi_i32 v176, v227, s34
	v_lshrrev_b32_e32 v177, 31, v176
	v_lshrrev_b32_e32 v176, 5, v176
	v_add_u32_e32 v176, v176, v177
	s_movk_i32 s34, 0xc0
	v_mul_lo_u32 v176, v176, s34
	v_sub_u32_e32 v176, v227, v176
	v_cmp_lt_i32_e32 vcc, 0x7f, v176
	v_add_u32_e32 v176, 0xffffff80, v176
	v_ashrrev_i32_e32 v214, 1, v176
	s_and_b64 s[0:1], vcc, exec
	s_and_saveexec_b64 s[8:9], s[0:1]
	s_cbranch_execz .Luq_nl_1_0
	v_mov_b32_e32 v216, v236
	v_and_b32_e32 v216, v216, v215
	v_mul_u32_u24_e32 v216, 32, v216
	v_add_lshl_u32 v216, v216, v214, 2
	global_load_dwordx4 v[152:155], v216, s[6:7]
	global_load_dwordx4 v[156:159], v216, s[4:5]
	v_add_u32_e32 v216, 0x10, v236
	v_and_b32_e32 v216, v216, v215
	v_mul_u32_u24_e32 v216, 32, v216
	v_add_lshl_u32 v216, v216, v214, 2
	global_load_dwordx4 v[144:147], v216, s[6:7]
	global_load_dwordx4 v[148:151], v216, s[4:5]
	v_add_u32_e32 v216, 0x20, v236
	v_and_b32_e32 v216, v216, v215
	v_mul_u32_u24_e32 v216, 32, v216
	v_add_lshl_u32 v216, v216, v214, 2
	global_load_dwordx4 v[140:143], v216, s[6:7]
	global_load_dwordx4 v[136:139], v216, s[4:5]
	v_add_u32_e32 v216, 0x30, v236
	v_and_b32_e32 v216, v216, v215
	v_mul_u32_u24_e32 v216, 32, v216
	v_add_lshl_u32 v216, v216, v214, 2
	global_load_dwordx4 v[128:131], v216, s[6:7]
	global_load_dwordx4 v[132:135], v216, s[4:5]
.Luq_nl_1_0:
	s_or_b64 exec, exec, s[8:9]
	v_mov_b32_e32 v184, v92
	v_mov_b32_e32 v185, v93
	v_mov_b32_e32 v186, v94
	v_mov_b32_e32 v187, v95
	v_mov_b32_e32 v188, v88
	v_mov_b32_e32 v189, v89
	v_mov_b32_e32 v190, v90
	v_mov_b32_e32 v191, v91
	s_and_saveexec_b64 s[8:9], s[0:1]
	s_cbranch_execz .Luq_nr_8
	s_waitcnt vmcnt(6)
	v_pk_mul_f32 v[186:187], v[156:157], v[92:93] op_sel:[0,1] op_sel_hi:[0,0]
	v_pk_fma_f32 v[188:189], v[152:153], v[92:93], v[186:187] op_sel_hi:[0,1,1]
	v_pk_fma_f32 v[184:185], v[152:153], v[92:93], v[186:187] op_sel_hi:[0,1,1] neg_lo:[0,0,1] neg_hi:[0,0,1]
	v_mov_b32_e32 v186, v153
	v_mov_b32_e32 v187, v157
	v_mul_f32_e32 v188, v157, v95
	v_pk_fma_f32 v[186:187], v[186:187], v[94:95], v[188:189] op_sel_hi:[1,1,0] neg_lo:[0,0,1] neg_hi:[0,0,1]
	v_mov_b32_e32 v190, v157
	v_mov_b32_e32 v191, v153
	v_mul_f32_e32 v188, v153, v95
	v_pk_fma_f32 v[190:191], v[190:191], v[94:95], v[188:189] op_sel_hi:[1,1,0]
	v_mov_b32_e32 v185, v189
	v_mov_b32_e32 v187, v190
	v_pk_mul_f32 v[190:191], v[158:159], v[88:89] op_sel:[0,1] op_sel_hi:[0,0]
	v_pk_fma_f32 v[188:189], v[154:155], v[88:89], v[190:191] op_sel_hi:[0,1,1] neg_lo:[0,0,1] neg_hi:[0,0,1]
	v_pk_fma_f32 v[224:225], v[154:155], v[88:89], v[190:191] op_sel_hi:[0,1,1]
	v_mov_b32_e32 v190, v155
	v_mov_b32_e32 v191, v159
	v_mul_f32_e32 v192, v159, v91
	v_pk_fma_f32 v[190:191], v[190:191], v[90:91], v[192:193] op_sel_hi:[1,1,0] neg_lo:[0,0,1] neg_hi:[0,0,1]
	v_mov_b32_e32 v226, v159
	v_mov_b32_e32 v227, v155
	v_mul_f32_e32 v192, v155, v91
	v_pk_fma_f32 v[226:227], v[226:227], v[90:91], v[192:193] op_sel_hi:[1,1,0]
	v_mov_b32_e32 v189, v225
	v_mov_b32_e32 v191, v226
;     __device__ __forceinline__ void operator()(const f32x4 (&acc)[2][2][4][2], const Unit& u, int wr, int wc, int fr_in, int fq_in) const {
;     ...
;                 if (rope) {
; #pragma unroll
;                     for (int m = 0; m < 4; ++m) { const int pos = row_pos(row0 + ai * HALF + m * 16); const unsigned tb = (unsigned)(pos * tw + i0) * 4u; rc[m] = *(const f32x4*)((const char*)cosT + tb); rsn[m] = *(const f32x4*)((const char*)sinT + tb); }
;                 }
; #pragma unroll
;                 for (int m = 0; m < 4; ++m) {
;                     const int row = row0 + ai * HALF + m * 16;
;                     f32x4 v0 = acc[ai][bj][m][0], v1 = acc[ai][bj][m][1];
;                     if (lnin) { const float mm = mu[ai * 4 + m], rr = rs[ai * 4 + m]; v0 = (v0 - cs0 * mm) * rr + bw0; v1 = (v1 - cs1 * mm) * rr + bw1; }
;                     if (mode == EM_F32) { const unsigned ob = (unsigned)(row * ldo + c) * 4u; *(f32x4*)((char*)Of + ob) = v0; *(f32x4*)((char*)Of + ob + 16u) = v1; }
;                     else {
;                         if (mode == EM_RELU2) {
; #pragma unroll
;                             for (int e = 0; e < 4; ++e) { const float a = fmaxf(v0[e], 0.f), b = fmaxf(v1[e], 0.f); v0[e] = a * a; v1[e] = b * b; }
;                         } else if (mode == EM_QKVA || mode == EM_UQ) {
;                             if (rope) {
;                                 const f32x4 cs_ = rc[m], sn = rsn[m];
;                                 f32x4 w0, w1;
;                                 w0[0] = v0[0] * cs_[0] - v0[1] * sn[0]; w0[1] = v0[1] * cs_[0] + v0[0] * sn[0];
;                                 w0[2] = v0[2] * cs_[1] - v0[3] * sn[1]; w0[3] = v0[3] * cs_[1] + v0[2] * sn[1];
;                                 w1[0] = v1[0] * cs_[2] - v1[1] * sn[2]; w1[1] = v1[1] * cs_[2] + v1[0] * sn[2];
;                                 w1[2] = v1[2] * cs_[3] - v1[3] * sn[3]; w1[3] = v1[3] * cs_[3] + v1[2] * sn[3];
;                                 v0 = w0; v1 = w1;
;                             }
;                             v0 = v0 * sc; v1 = v1 * sc;
;                         }
;                         u32x4 w; w.x = cvt_pk_bf16(v0[0], v0[1]); w.y = cvt_pk_bf16(v0[2], v0[3]); w.z = cvt_pk_bf16(v1[0], v1[1]); w.w = cvt_pk_bf16(v1[2], v1[3]);
.Luq_nr_8:
	s_or_b64 exec, exec, s[8:9]
	v_pk_mul_f32 v[224:225], v[234:235], v[186:187]
	v_pk_mul_f32 v[226:227], v[234:235], v[184:185]
	v_pk_mul_f32 v[184:185], v[234:235], v[190:191]
	v_pk_mul_f32 v[186:187], v[234:235], v[188:189]
	v_cvt_pk_bf16_f32 v160, v226, v227
	v_cvt_pk_bf16_f32 v161, v224, v225
	v_cvt_pk_bf16_f32 v162, v186, v187
	v_cvt_pk_bf16_f32 v163, v184, v185
	global_store_dwordx4 v206, v[160:163], s[50:51] offset:256
	v_mov_b32_e32 v184, v84
	v_mov_b32_e32 v185, v85
	v_mov_b32_e32 v186, v86
	v_mov_b32_e32 v187, v87
	v_mov_b32_e32 v188, v80
	v_mov_b32_e32 v189, v81
	v_mov_b32_e32 v190, v82
	v_mov_b32_e32 v191, v83
	s_and_saveexec_b64 s[8:9], s[0:1]
	s_cbranch_execz .Luq_nr_9
	s_waitcnt vmcnt(5)
	v_pk_mul_f32 v[186:187], v[148:149], v[84:85] op_sel:[0,1] op_sel_hi:[0,0]
	v_pk_fma_f32 v[188:189], v[144:145], v[84:85], v[186:187] op_sel_hi:[0,1,1]
	v_pk_fma_f32 v[184:185], v[144:145], v[84:85], v[186:187] op_sel_hi:[0,1,1] neg_lo:[0,0,1] neg_hi:[0,0,1]
	v_mov_b32_e32 v186, v145
	v_mov_b32_e32 v187, v149
	v_mul_f32_e32 v188, v149, v87
	v_pk_fma_f32 v[186:187], v[186:187], v[86:87], v[188:189] op_sel_hi:[1,1,0] neg_lo:[0,0,1] neg_hi:[0,0,1]
	v_mov_b32_e32 v190, v149
	v_mov_b32_e32 v191, v145
	v_mul_f32_e32 v188, v145, v87
	v_pk_fma_f32 v[190:191], v[190:191], v[86:87], v[188:189] op_sel_hi:[1,1,0]
	v_mov_b32_e32 v185, v189
	v_mov_b32_e32 v187, v190
	v_pk_mul_f32 v[190:191], v[150:151], v[80:81] op_sel:[0,1] op_sel_hi:[0,0]
	v_pk_fma_f32 v[188:189], v[146:147], v[80:81], v[190:191] op_sel_hi:[0,1,1] neg_lo:[0,0,1] neg_hi:[0,0,1]
	v_pk_fma_f32 v[224:225], v[146:147], v[80:81], v[190:191] op_sel_hi:[0,1,1]
	v_mov_b32_e32 v190, v147
	v_mov_b32_e32 v191, v151
	v_mul_f32_e32 v192, v151, v83
	v_pk_fma_f32 v[190:191], v[190:191], v[82:83], v[192:193] op_sel_hi:[1,1,0] neg_lo:[0,0,1] neg_hi:[0,0,1]
	v_mov_b32_e32 v226, v151
	v_mov_b32_e32 v227, v147
	v_mul_f32_e32 v192, v147, v83
	v_pk_fma_f32 v[226:227], v[226:227], v[82:83], v[192:193] op_sel_hi:[1,1,0]
	v_mov_b32_e32 v189, v225
	v_mov_b32_e32 v191, v226
.Luq_nr_9:
	s_or_b64 exec, exec, s[8:9]
	v_pk_mul_f32 v[224:225], v[234:235], v[186:187]
	v_pk_mul_f32 v[226:227], v[234:235], v[184:185]
	v_pk_mul_f32 v[184:185], v[234:235], v[190:191]
	v_pk_mul_f32 v[186:187], v[234:235], v[188:189]
	v_cvt_pk_bf16_f32 v164, v226, v227
	v_cvt_pk_bf16_f32 v165, v224, v225
	v_cvt_pk_bf16_f32 v166, v186, v187
	v_cvt_pk_bf16_f32 v167, v184, v185
	global_store_dwordx4 v207, v[164:167], s[50:51] offset:256
	v_mov_b32_e32 v184, v76
	v_mov_b32_e32 v185, v77
	v_mov_b32_e32 v186, v78
	v_mov_b32_e32 v187, v79
	v_mov_b32_e32 v188, v72
	v_mov_b32_e32 v189, v73
	v_mov_b32_e32 v190, v74
	v_mov_b32_e32 v191, v75
	s_and_saveexec_b64 s[8:9], s[0:1]
	s_cbranch_execz .Luq_nr_10
	s_waitcnt vmcnt(4)
	v_pk_mul_f32 v[186:187], v[136:137], v[76:77] op_sel:[0,1] op_sel_hi:[0,0]
	v_pk_fma_f32 v[188:189], v[140:141], v[76:77], v[186:187] op_sel_hi:[0,1,1]
	v_pk_fma_f32 v[184:185], v[140:141], v[76:77], v[186:187] op_sel_hi:[0,1,1] neg_lo:[0,0,1] neg_hi:[0,0,1]
	v_mov_b32_e32 v186, v141
	v_mov_b32_e32 v187, v137
	v_mul_f32_e32 v188, v137, v79
	v_pk_fma_f32 v[186:187], v[186:187], v[78:79], v[188:189] op_sel_hi:[1,1,0] neg_lo:[0,0,1] neg_hi:[0,0,1]
	v_mov_b32_e32 v190, v137
	v_mov_b32_e32 v191, v141
	v_mul_f32_e32 v188, v141, v79
	v_pk_fma_f32 v[190:191], v[190:191], v[78:79], v[188:189] op_sel_hi:[1,1,0]
	v_mov_b32_e32 v185, v189
	v_mov_b32_e32 v187, v190
	v_pk_mul_f32 v[190:191], v[138:139], v[72:73] op_sel:[0,1] op_sel_hi:[0,0]
	v_pk_fma_f32 v[188:189], v[142:143], v[72:73], v[190:191] op_sel_hi:[0,1,1] neg_lo:[0,0,1] neg_hi:[0,0,1]
	v_pk_fma_f32 v[224:225], v[142:143], v[72:73], v[190:191] op_sel_hi:[0,1,1]
	v_mov_b32_e32 v190, v143
	v_mov_b32_e32 v191, v139
	v_mul_f32_e32 v192, v139, v75
	v_pk_fma_f32 v[190:191], v[190:191], v[74:75], v[192:193] op_sel_hi:[1,1,0] neg_lo:[0,0,1] neg_hi:[0,0,1]
	v_mov_b32_e32 v226, v139
	v_mov_b32_e32 v227, v143
	v_mul_f32_e32 v192, v143, v75
	v_pk_fma_f32 v[226:227], v[226:227], v[74:75], v[192:193] op_sel_hi:[1,1,0]
	v_mov_b32_e32 v189, v225
	v_mov_b32_e32 v191, v226
.Luq_nr_10:
	s_or_b64 exec, exec, s[8:9]
	v_pk_mul_f32 v[224:225], v[234:235], v[186:187]
	v_pk_mul_f32 v[226:227], v[234:235], v[184:185]
	v_pk_mul_f32 v[184:185], v[234:235], v[190:191]
	v_pk_mul_f32 v[186:187], v[234:235], v[188:189]
	v_cvt_pk_bf16_f32 v168, v226, v227
	v_cvt_pk_bf16_f32 v169, v224, v225
	v_cvt_pk_bf16_f32 v170, v186, v187
	v_cvt_pk_bf16_f32 v171, v184, v185
	global_store_dwordx4 v208, v[168:171], s[50:51] offset:256
	v_mov_b32_e32 v184, v68
	v_mov_b32_e32 v185, v69
	v_mov_b32_e32 v186, v70
	v_mov_b32_e32 v187, v71
	v_mov_b32_e32 v188, v64
	v_mov_b32_e32 v189, v65
	v_mov_b32_e32 v190, v66
	v_mov_b32_e32 v191, v67
	s_and_saveexec_b64 s[8:9], s[0:1]
	s_cbranch_execz .Luq_nr_11
	s_waitcnt vmcnt(3)
	v_pk_mul_f32 v[186:187], v[132:133], v[68:69] op_sel:[0,1] op_sel_hi:[0,0]
	v_pk_fma_f32 v[188:189], v[128:129], v[68:69], v[186:187] op_sel_hi:[0,1,1]
	v_pk_fma_f32 v[184:185], v[128:129], v[68:69], v[186:187] op_sel_hi:[0,1,1] neg_lo:[0,0,1] neg_hi:[0,0,1]
	v_mov_b32_e32 v186, v129
	v_mov_b32_e32 v187, v133
	v_mul_f32_e32 v188, v133, v71
	v_pk_fma_f32 v[186:187], v[186:187], v[70:71], v[188:189] op_sel_hi:[1,1,0] neg_lo:[0,0,1] neg_hi:[0,0,1]
	v_mov_b32_e32 v190, v133
	v_mov_b32_e32 v191, v129
	v_mul_f32_e32 v188, v129, v71
	v_pk_fma_f32 v[190:191], v[190:191], v[70:71], v[188:189] op_sel_hi:[1,1,0]
	v_mov_b32_e32 v185, v189
	v_mov_b32_e32 v187, v190
	v_pk_mul_f32 v[190:191], v[134:135], v[64:65] op_sel:[0,1] op_sel_hi:[0,0]
	v_pk_fma_f32 v[188:189], v[130:131], v[64:65], v[190:191] op_sel_hi:[0,1,1] neg_lo:[0,0,1] neg_hi:[0,0,1]
	v_pk_fma_f32 v[224:225], v[130:131], v[64:65], v[190:191] op_sel_hi:[0,1,1]
	v_mov_b32_e32 v190, v131
	v_mov_b32_e32 v191, v135
	v_mul_f32_e32 v192, v135, v67
	v_pk_fma_f32 v[190:191], v[190:191], v[66:67], v[192:193] op_sel_hi:[1,1,0] neg_lo:[0,0,1] neg_hi:[0,0,1]
	v_mov_b32_e32 v226, v135
	v_mov_b32_e32 v227, v131
	v_mul_f32_e32 v192, v131, v67
	v_pk_fma_f32 v[226:227], v[226:227], v[66:67], v[192:193] op_sel_hi:[1,1,0]
	v_mov_b32_e32 v189, v225
	v_mov_b32_e32 v191, v226
;     __device__ __forceinline__ void operator()(const f32x4 (&acc)[2][2][4][2], const Unit& u, int wr, int wc, int fr_in, int fq_in) const {
;     ...
;                 if (rope) {
; #pragma unroll
;                     for (int m = 0; m < 4; ++m) { const int pos = row_pos(row0 + ai * HALF + m * 16); const unsigned tb = (unsigned)(pos * tw + i0) * 4u; rc[m] = *(const f32x4*)((const char*)cosT + tb); rsn[m] = *(const f32x4*)((const char*)sinT + tb); }
;                 }
; #pragma unroll
;                 for (int m = 0; m < 4; ++m) {
;                     const int row = row0 + ai * HALF + m * 16;
;                     f32x4 v0 = acc[ai][bj][m][0], v1 = acc[ai][bj][m][1];
;                     if (lnin) { const float mm = mu[ai * 4 + m], rr = rs[ai * 4 + m]; v0 = (v0 - cs0 * mm) * rr + bw0; v1 = (v1 - cs1 * mm) * rr + bw1; }
;                     if (mode == EM_F32) { const unsigned ob = (unsigned)(row * ldo + c) * 4u; *(f32x4*)((char*)Of + ob) = v0; *(f32x4*)((char*)Of + ob + 16u) = v1; }
;                     else {
;                         if (mode == EM_RELU2) {
; #pragma unroll
;                             for (int e = 0; e < 4; ++e) { const float a = fmaxf(v0[e], 0.f), b = fmaxf(v1[e], 0.f); v0[e] = a * a; v1[e] = b * b; }
;                         } else if (mode == EM_QKVA || mode == EM_UQ) {
;                             if (rope) {
;                                 const f32x4 cs_ = rc[m], sn = rsn[m];
;                                 f32x4 w0, w1;
;                                 w0[0] = v0[0] * cs_[0] - v0[1] * sn[0]; w0[1] = v0[1] * cs_[0] + v0[0] * sn[0];
;                                 w0[2] = v0[2] * cs_[1] - v0[3] * sn[1]; w0[3] = v0[3] * cs_[1] + v0[2] * sn[1];
;                                 w1[0] = v1[0] * cs_[2] - v1[1] * sn[2]; w1[1] = v1[1] * cs_[2] + v1[0] * sn[2];
;                                 w1[2] = v1[2] * cs_[3] - v1[3] * sn[3]; w1[3] = v1[3] * cs_[3] + v1[2] * sn[3];
;                                 v0 = w0; v1 = w1;
;                             }
;                             v0 = v0 * sc; v1 = v1 * sc;
;                         }
;                         u32x4 w; w.x = cvt_pk_bf16(v0[0], v0[1]); w.y = cvt_pk_bf16(v0[2], v0[3]); w.z = cvt_pk_bf16(v1[0], v1[1]); w.w = cvt_pk_bf16(v1[2], v1[3]);
.Luq_nr_11:
	s_or_b64 exec, exec, s[8:9]
	v_pk_mul_f32 v[224:225], v[234:235], v[186:187]
	v_pk_mul_f32 v[226:227], v[234:235], v[184:185]
	v_pk_mul_f32 v[184:185], v[234:235], v[190:191]
	v_pk_mul_f32 v[186:187], v[234:235], v[188:189]
	v_cvt_pk_bf16_f32 v172, v226, v227
	v_cvt_pk_bf16_f32 v173, v224, v225
	v_cvt_pk_bf16_f32 v174, v186, v187
	v_cvt_pk_bf16_f32 v175, v184, v185
	global_store_dwordx4 v209, v[172:175], s[50:51] offset:256
	s_and_saveexec_b64 s[8:9], s[0:1]
	s_cbranch_execz .Luq_nl_1_1
	v_add_u32_e32 v216, 0x80, v236
	v_and_b32_e32 v216, v216, v215
	v_mul_u32_u24_e32 v216, 32, v216
	v_add_lshl_u32 v216, v216, v214, 2
	global_load_dwordx4 v[152:155], v216, s[6:7]
	global_load_dwordx4 v[156:159], v216, s[4:5]
	v_add_u32_e32 v216, 0x90, v236
	v_and_b32_e32 v216, v216, v215
	v_mul_u32_u24_e32 v216, 32, v216
	v_add_lshl_u32 v216, v216, v214, 2
	global_load_dwordx4 v[144:147], v216, s[6:7]
	global_load_dwordx4 v[148:151], v216, s[4:5]
	v_add_u32_e32 v216, 0xa0, v236
	v_and_b32_e32 v216, v216, v215
	v_mul_u32_u24_e32 v216, 32, v216
	v_add_lshl_u32 v216, v216, v214, 2
	global_load_dwordx4 v[140:143], v216, s[6:7]
	global_load_dwordx4 v[136:139], v216, s[4:5]
	v_add_u32_e32 v216, 0xb0, v236
	v_and_b32_e32 v216, v216, v215
	v_mul_u32_u24_e32 v216, 32, v216
	v_add_lshl_u32 v216, v216, v214, 2
	global_load_dwordx4 v[128:131], v216, s[6:7]
	global_load_dwordx4 v[132:135], v216, s[4:5]
.Luq_nl_1_1:
	s_or_b64 exec, exec, s[8:9]
	v_mov_b32_e32 v184, v28
	v_mov_b32_e32 v185, v29
	v_mov_b32_e32 v186, v30
	v_mov_b32_e32 v187, v31
	v_mov_b32_e32 v188, v24
	v_mov_b32_e32 v189, v25
	v_mov_b32_e32 v190, v26
	v_mov_b32_e32 v191, v27
	s_and_saveexec_b64 s[8:9], s[0:1]
	s_cbranch_execz .Luq_nr_12
	s_waitcnt vmcnt(6)
	v_pk_mul_f32 v[186:187], v[156:157], v[28:29] op_sel:[0,1] op_sel_hi:[0,0]
	v_pk_fma_f32 v[188:189], v[152:153], v[28:29], v[186:187] op_sel_hi:[0,1,1]
	v_pk_fma_f32 v[184:185], v[152:153], v[28:29], v[186:187] op_sel_hi:[0,1,1] neg_lo:[0,0,1] neg_hi:[0,0,1]
	v_mov_b32_e32 v186, v153
	v_mov_b32_e32 v187, v157
	v_mul_f32_e32 v188, v157, v31
	v_pk_fma_f32 v[186:187], v[186:187], v[30:31], v[188:189] op_sel_hi:[1,1,0] neg_lo:[0,0,1] neg_hi:[0,0,1]
	v_mov_b32_e32 v190, v157
	v_mov_b32_e32 v191, v153
	v_mul_f32_e32 v188, v153, v31
	v_pk_fma_f32 v[190:191], v[190:191], v[30:31], v[188:189] op_sel_hi:[1,1,0]
	v_mov_b32_e32 v185, v189
	v_mov_b32_e32 v187, v190
	v_pk_mul_f32 v[190:191], v[158:159], v[24:25] op_sel:[0,1] op_sel_hi:[0,0]
	v_pk_fma_f32 v[188:189], v[154:155], v[24:25], v[190:191] op_sel_hi:[0,1,1] neg_lo:[0,0,1] neg_hi:[0,0,1]
	v_pk_fma_f32 v[224:225], v[154:155], v[24:25], v[190:191] op_sel_hi:[0,1,1]
	v_mov_b32_e32 v190, v155
	v_mov_b32_e32 v191, v159
	v_mul_f32_e32 v192, v159, v27
	v_pk_fma_f32 v[190:191], v[190:191], v[26:27], v[192:193] op_sel_hi:[1,1,0] neg_lo:[0,0,1] neg_hi:[0,0,1]
	v_mov_b32_e32 v226, v159
	v_mov_b32_e32 v227, v155
	v_mul_f32_e32 v192, v155, v27
	v_pk_fma_f32 v[226:227], v[226:227], v[26:27], v[192:193] op_sel_hi:[1,1,0]
	v_mov_b32_e32 v189, v225
	v_mov_b32_e32 v191, v226
.Luq_nr_12:
	s_or_b64 exec, exec, s[8:9]
	v_pk_mul_f32 v[224:225], v[234:235], v[186:187]
	v_pk_mul_f32 v[226:227], v[234:235], v[184:185]
	v_pk_mul_f32 v[184:185], v[234:235], v[190:191]
	v_pk_mul_f32 v[186:187], v[234:235], v[188:189]
	v_cvt_pk_bf16_f32 v160, v226, v227
	v_cvt_pk_bf16_f32 v161, v224, v225
	v_cvt_pk_bf16_f32 v162, v186, v187
	v_cvt_pk_bf16_f32 v163, v184, v185
	global_store_dwordx4 v210, v[160:163], s[50:51] offset:256
	v_mov_b32_e32 v184, v20
	v_mov_b32_e32 v185, v21
	v_mov_b32_e32 v186, v22
	v_mov_b32_e32 v187, v23
	v_mov_b32_e32 v188, v16
	v_mov_b32_e32 v189, v17
	v_mov_b32_e32 v190, v18
	v_mov_b32_e32 v191, v19
	s_and_saveexec_b64 s[8:9], s[0:1]
	s_cbranch_execz .Luq_nr_13
	s_waitcnt vmcnt(5)
	v_pk_mul_f32 v[186:187], v[148:149], v[20:21] op_sel:[0,1] op_sel_hi:[0,0]
	v_pk_fma_f32 v[188:189], v[144:145], v[20:21], v[186:187] op_sel_hi:[0,1,1]
	v_pk_fma_f32 v[184:185], v[144:145], v[20:21], v[186:187] op_sel_hi:[0,1,1] neg_lo:[0,0,1] neg_hi:[0,0,1]
	v_mov_b32_e32 v186, v145
	v_mov_b32_e32 v187, v149
	v_mul_f32_e32 v188, v149, v23
	v_pk_fma_f32 v[186:187], v[186:187], v[22:23], v[188:189] op_sel_hi:[1,1,0] neg_lo:[0,0,1] neg_hi:[0,0,1]
	v_mov_b32_e32 v190, v149
	v_mov_b32_e32 v191, v145
	v_mul_f32_e32 v188, v145, v23
	v_pk_fma_f32 v[190:191], v[190:191], v[22:23], v[188:189] op_sel_hi:[1,1,0]
	v_mov_b32_e32 v185, v189
	v_mov_b32_e32 v187, v190
	v_pk_mul_f32 v[190:191], v[150:151], v[16:17] op_sel:[0,1] op_sel_hi:[0,0]
	v_pk_fma_f32 v[188:189], v[146:147], v[16:17], v[190:191] op_sel_hi:[0,1,1] neg_lo:[0,0,1] neg_hi:[0,0,1]
	v_pk_fma_f32 v[224:225], v[146:147], v[16:17], v[190:191] op_sel_hi:[0,1,1]
	v_mov_b32_e32 v190, v147
	v_mov_b32_e32 v191, v151
	v_mul_f32_e32 v192, v151, v19
	v_pk_fma_f32 v[190:191], v[190:191], v[18:19], v[192:193] op_sel_hi:[1,1,0] neg_lo:[0,0,1] neg_hi:[0,0,1]
	v_mov_b32_e32 v226, v151
	v_mov_b32_e32 v227, v147
	v_mul_f32_e32 v192, v147, v19
	v_pk_fma_f32 v[226:227], v[226:227], v[18:19], v[192:193] op_sel_hi:[1,1,0]
	v_mov_b32_e32 v189, v225
	v_mov_b32_e32 v191, v226
;     __device__ __forceinline__ void operator()(const f32x4 (&acc)[2][2][4][2], const Unit& u, int wr, int wc, int fr_in, int fq_in) const {
;     ...
;                 if (rope) {
; #pragma unroll
;                     for (int m = 0; m < 4; ++m) { const int pos = row_pos(row0 + ai * HALF + m * 16); const unsigned tb = (unsigned)(pos * tw + i0) * 4u; rc[m] = *(const f32x4*)((const char*)cosT + tb); rsn[m] = *(const f32x4*)((const char*)sinT + tb); }
;                 }
; #pragma unroll
;                 for (int m = 0; m < 4; ++m) {
;                     const int row = row0 + ai * HALF + m * 16;
;                     f32x4 v0 = acc[ai][bj][m][0], v1 = acc[ai][bj][m][1];
;                     if (lnin) { const float mm = mu[ai * 4 + m], rr = rs[ai * 4 + m]; v0 = (v0 - cs0 * mm) * rr + bw0; v1 = (v1 - cs1 * mm) * rr + bw1; }
;                     if (mode == EM_F32) { const unsigned ob = (unsigned)(row * ldo + c) * 4u; *(f32x4*)((char*)Of + ob) = v0; *(f32x4*)((char*)Of + ob + 16u) = v1; }
;                     else {
;                         if (mode == EM_RELU2) {
; #pragma unroll
;                             for (int e = 0; e < 4; ++e) { const float a = fmaxf(v0[e], 0.f), b = fmaxf(v1[e], 0.f); v0[e] = a * a; v1[e] = b * b; }
;                         } else if (mode == EM_QKVA || mode == EM_UQ) {
;                             if (rope) {
;                                 const f32x4 cs_ = rc[m], sn = rsn[m];
;                                 f32x4 w0, w1;
;                                 w0[0] = v0[0] * cs_[0] - v0[1] * sn[0]; w0[1] = v0[1] * cs_[0] + v0[0] * sn[0];
;                                 w0[2] = v0[2] * cs_[1] - v0[3] * sn[1]; w0[3] = v0[3] * cs_[1] + v0[2] * sn[1];
;                                 w1[0] = v1[0] * cs_[2] - v1[1] * sn[2]; w1[1] = v1[1] * cs_[2] + v1[0] * sn[2];
;                                 w1[2] = v1[2] * cs_[3] - v1[3] * sn[3]; w1[3] = v1[3] * cs_[3] + v1[2] * sn[3];
;                                 v0 = w0; v1 = w1;
;                             }
;                             v0 = v0 * sc; v1 = v1 * sc;
;                         }
;                         u32x4 w; w.x = cvt_pk_bf16(v0[0], v0[1]); w.y = cvt_pk_bf16(v0[2], v0[3]); w.z = cvt_pk_bf16(v1[0], v1[1]); w.w = cvt_pk_bf16(v1[2], v1[3]);
.Luq_nr_13:
	s_or_b64 exec, exec, s[8:9]
	v_pk_mul_f32 v[224:225], v[234:235], v[186:187]
	v_pk_mul_f32 v[226:227], v[234:235], v[184:185]
	v_pk_mul_f32 v[184:185], v[234:235], v[190:191]
	v_pk_mul_f32 v[186:187], v[234:235], v[188:189]
	v_cvt_pk_bf16_f32 v164, v226, v227
	v_cvt_pk_bf16_f32 v165, v224, v225
	v_cvt_pk_bf16_f32 v166, v186, v187
	v_cvt_pk_bf16_f32 v167, v184, v185
	global_store_dwordx4 v211, v[164:167], s[50:51] offset:256
	v_mov_b32_e32 v184, v12
	v_mov_b32_e32 v185, v13
	v_mov_b32_e32 v186, v14
	v_mov_b32_e32 v187, v15
	v_mov_b32_e32 v188, v8
	v_mov_b32_e32 v189, v9
	v_mov_b32_e32 v190, v10
	v_mov_b32_e32 v191, v11
	s_and_saveexec_b64 s[8:9], s[0:1]
	s_cbranch_execz .Luq_nr_14
	s_waitcnt vmcnt(4)
	v_pk_mul_f32 v[186:187], v[136:137], v[12:13] op_sel:[0,1] op_sel_hi:[0,0]
	v_pk_fma_f32 v[188:189], v[140:141], v[12:13], v[186:187] op_sel_hi:[0,1,1]
	v_pk_fma_f32 v[184:185], v[140:141], v[12:13], v[186:187] op_sel_hi:[0,1,1] neg_lo:[0,0,1] neg_hi:[0,0,1]
	v_mov_b32_e32 v186, v141
	v_mov_b32_e32 v187, v137
	v_mul_f32_e32 v188, v137, v15
	v_pk_fma_f32 v[186:187], v[186:187], v[14:15], v[188:189] op_sel_hi:[1,1,0] neg_lo:[0,0,1] neg_hi:[0,0,1]
	v_mov_b32_e32 v190, v137
	v_mov_b32_e32 v191, v141
	v_mul_f32_e32 v188, v141, v15
	v_pk_fma_f32 v[190:191], v[190:191], v[14:15], v[188:189] op_sel_hi:[1,1,0]
	v_mov_b32_e32 v185, v189
	v_mov_b32_e32 v187, v190
	v_pk_mul_f32 v[190:191], v[138:139], v[8:9] op_sel:[0,1] op_sel_hi:[0,0]
	v_pk_fma_f32 v[188:189], v[142:143], v[8:9], v[190:191] op_sel_hi:[0,1,1] neg_lo:[0,0,1] neg_hi:[0,0,1]
	v_pk_fma_f32 v[224:225], v[142:143], v[8:9], v[190:191] op_sel_hi:[0,1,1]
	v_mov_b32_e32 v190, v143
	v_mov_b32_e32 v191, v139
	v_mul_f32_e32 v192, v139, v11
	v_pk_fma_f32 v[190:191], v[190:191], v[10:11], v[192:193] op_sel_hi:[1,1,0] neg_lo:[0,0,1] neg_hi:[0,0,1]
	v_mov_b32_e32 v226, v139
	v_mov_b32_e32 v227, v143
	v_mul_f32_e32 v192, v143, v11
	v_pk_fma_f32 v[226:227], v[226:227], v[10:11], v[192:193] op_sel_hi:[1,1,0]
	v_mov_b32_e32 v189, v225
	v_mov_b32_e32 v191, v226
.Luq_nr_14:
	s_or_b64 exec, exec, s[8:9]
	v_pk_mul_f32 v[224:225], v[234:235], v[186:187]
	v_pk_mul_f32 v[226:227], v[234:235], v[184:185]
	v_pk_mul_f32 v[184:185], v[234:235], v[190:191]
	v_pk_mul_f32 v[186:187], v[234:235], v[188:189]
	v_cvt_pk_bf16_f32 v168, v226, v227
	v_cvt_pk_bf16_f32 v169, v224, v225
	v_cvt_pk_bf16_f32 v170, v186, v187
	v_cvt_pk_bf16_f32 v171, v184, v185
	global_store_dwordx4 v212, v[168:171], s[50:51] offset:256
	v_mov_b32_e32 v184, v4
	v_mov_b32_e32 v185, v5
	v_mov_b32_e32 v186, v6
	v_mov_b32_e32 v187, v7
	v_mov_b32_e32 v188, v0
	v_mov_b32_e32 v189, v1
	v_mov_b32_e32 v190, v2
	v_mov_b32_e32 v191, v3
	s_and_saveexec_b64 s[8:9], s[0:1]
	s_cbranch_execz .Luq_nr_15
	s_waitcnt vmcnt(3)
	v_pk_mul_f32 v[186:187], v[132:133], v[4:5] op_sel:[0,1] op_sel_hi:[0,0]
	v_pk_fma_f32 v[188:189], v[128:129], v[4:5], v[186:187] op_sel_hi:[0,1,1]
	v_pk_fma_f32 v[184:185], v[128:129], v[4:5], v[186:187] op_sel_hi:[0,1,1] neg_lo:[0,0,1] neg_hi:[0,0,1]
	v_mov_b32_e32 v186, v129
	v_mov_b32_e32 v187, v133
	v_mul_f32_e32 v188, v133, v7
	v_pk_fma_f32 v[186:187], v[186:187], v[6:7], v[188:189] op_sel_hi:[1,1,0] neg_lo:[0,0,1] neg_hi:[0,0,1]
	v_mov_b32_e32 v190, v133
	v_mov_b32_e32 v191, v129
	v_mul_f32_e32 v188, v129, v7
	v_pk_fma_f32 v[190:191], v[190:191], v[6:7], v[188:189] op_sel_hi:[1,1,0]
	v_mov_b32_e32 v185, v189
	v_mov_b32_e32 v187, v190
	v_pk_mul_f32 v[190:191], v[134:135], v[0:1] op_sel:[0,1] op_sel_hi:[0,0]
	v_pk_fma_f32 v[188:189], v[130:131], v[0:1], v[190:191] op_sel_hi:[0,1,1] neg_lo:[0,0,1] neg_hi:[0,0,1]
	v_pk_fma_f32 v[224:225], v[130:131], v[0:1], v[190:191] op_sel_hi:[0,1,1]
	v_mov_b32_e32 v190, v131
	v_mov_b32_e32 v191, v135
	v_mul_f32_e32 v192, v135, v3
	v_pk_fma_f32 v[190:191], v[190:191], v[2:3], v[192:193] op_sel_hi:[1,1,0] neg_lo:[0,0,1] neg_hi:[0,0,1]
	v_mov_b32_e32 v226, v135
	v_mov_b32_e32 v227, v131
	v_mul_f32_e32 v192, v131, v3
	v_pk_fma_f32 v[226:227], v[226:227], v[2:3], v[192:193] op_sel_hi:[1,1,0]
	v_mov_b32_e32 v189, v225
	v_mov_b32_e32 v191, v226
.Luq_nr_15:
	s_or_b64 exec, exec, s[8:9]
	v_pk_mul_f32 v[224:225], v[234:235], v[186:187]
	v_pk_mul_f32 v[226:227], v[234:235], v[184:185]
	v_pk_mul_f32 v[184:185], v[234:235], v[190:191]
	v_pk_mul_f32 v[186:187], v[234:235], v[188:189]
	v_cvt_pk_bf16_f32 v172, v226, v227
	v_cvt_pk_bf16_f32 v173, v224, v225
	v_cvt_pk_bf16_f32 v174, v186, v187
	v_cvt_pk_bf16_f32 v175, v184, v185
	global_store_dwordx4 v213, v[172:175], s[50:51] offset:256
	s_branch .LBB0_736
